# A/B GLU assignment + 10.5 us lag of the odd (no-GLU) panels
# speedup vs baseline: 1.0004x; 1.0004x over previous
.LBB0_589:
	s_cmp_gt_i32 s26, 4
	s_cselect_b64 s[4:5], -1, 0
	s_xor_b64 s[0:1], s[0:1], -1
	s_or_b64 s[0:1], s[4:5], s[0:1]
	s_and_b64 vcc, exec, s[0:1]
	s_cbranch_vccnz .LBB0_771
	s_bitcmp0_b32 s96, 3
	s_cbranch_scc1 .Lp4_lag
	s_sleep 127
	s_sleep 127
	s_sleep 127
.Lp4_lag:
	v_and_b32_e32 v231, 0x3ff, v0
	v_lshlrev_b32_e32 v1, 4, v231
	v_and_b32_e32 v2, 32, v0
	v_bitop3_b32 v229, v1, v2, 48 bitop3:0x6c
	v_lshrrev_b32_e32 v2, 5, v0
	v_lshrrev_b32_e32 v4, 1, v0
	v_and_b32_e32 v2, 4, v2
	v_bfe_u32 v3, v231, 2, 2
	v_and_b32_e32 v236, 24, v4
	v_bfe_u32 v232, v231, 2, 4
	v_and_b32_e32 v230, 64, v0
	v_or3_b32 v2, v2, v3, v236
	v_bfe_u32 v0, v0, 3, 7
	v_or_b32_e32 v233, 0x2000, v1
	v_and_or_b32 v240, v0, 48, v232
	v_and_or_b32 v241, v0, 32, v2
	v_lshrrev_b32_e32 v0, 7, v233
	s_movk_i32 s1, 0x70
	v_and_or_b32 v243, v0, s1, v232
	s_movk_i32 s1, 0x60
	v_and_or_b32 v242, v0, s1, v2
	v_lshlrev_b32_e32 v0, 6, v231
	s_add_u32 s4, s76, 0x1000000
	v_and_b32_e32 v234, 0x3c0, v0
	v_lshlrev_b32_e32 v0, 2, v231
	s_addc_u32 s40, s77, 0
	v_or_b32_e32 v239, v229, v230
	v_lshlrev_b32_e32 v237, 1, v236
	v_and_b32_e32 v235, 32, v0
	v_readfirstlane_b32 s0, v231
	v_lshl_or_b32 v208, v240, 10, v239
	v_lshl_or_b32 v210, v241, 10, v239
	v_lshl_or_b32 v212, v243, 10, v239
	v_lshl_or_b32 v214, v242, 10, v239
	s_bitcmp1_b32 s96, 3
	v_bitop3_b32 v238, v237, v235, v234 bitop3:0x36
	s_cbranch_scc1 .LBB0_610
	s_lshl_b32 s2, s96, 3
	s_and_b32 s2, s2, 56
	s_bfe_u32 s6, s96, 0x30003
	s_lshr_b32 s5, s0, 6
	s_or_b32 s2, s2, s6
	s_bfe_u32 s6, s96, 0x50006
	s_lshr_b32 s98, s96, 7
	s_add_i32 s2, s2, s98
	s_and_b32 s6, s6, 1
	s_lshr_b32 s1, s0, 8
	s_lshl_b32 s33, s5, 10
	s_lshl_b32 s7, s2, 18
	s_lshl_b32 s8, s6, 18
	s_add_u32 s36, s78, s8
	s_addc_u32 s37, s79, 0
	s_add_i32 s41, s33, 0
	s_add_i32 m0, s41, 0x10000
	v_mov_b32_e32 v211, 0
	global_load_lds_dwordx4 v210, s[36:37]
	s_add_i32 m0, s41, 0x12000
	s_add_u32 s8, s36, 0x20000
	global_load_lds_dwordx4 v214, s[36:37]
	s_addc_u32 s9, s37, 0
	s_add_i32 m0, s41, 0x14000
	v_mov_b32_e32 v215, v211
	global_load_lds_dwordx4 v210, s[8:9]
	s_add_i32 m0, s41, 0x16000
	s_add_u32 s34, s76, s7
	s_addc_u32 s35, s77, 0
	s_add_i32 s42, s41, 0x2000
	global_load_lds_dwordx4 v214, s[8:9]
	s_mov_b32 m0, s41
	s_add_u32 s8, s34, 0x20000
	global_load_lds_dwordx4 v208, s[34:35]
	s_mov_b32 m0, s42
	s_addc_u32 s9, s35, 0
	s_add_i32 s43, s41, 0x4000
	global_load_lds_dwordx4 v212, s[34:35]
	s_mov_b32 m0, s43
	s_add_i32 s44, s41, 0x6000
	global_load_lds_dwordx4 v208, s[8:9]
	s_mov_b32 m0, s44
	v_mov_b32_e32 v209, v211
	global_load_lds_dwordx4 v212, s[8:9]
	v_mov_b32_e32 v213, v211
	s_cmp_eq_u32 s1, 1
	s_mov_b32 s45, 0
	v_lshl_add_u64 v[6:7], s[36:37], 0, v[210:211]
	v_lshl_add_u64 v[2:3], s[36:37], 0, v[214:215]
	s_mov_b64 s[8:9], 0x20000
	v_lshl_add_u64 v[0:1], s[34:35], 0, v[208:209]
	s_cselect_b64 s[10:11], -1, 0
	s_cmp_lg_u32 s1, 1
	v_lshl_add_u64 v[4:5], s[34:35], 0, v[212:213]
	s_cbranch_scc1 .LBB0_593
	s_barrier
